# v72 + workgroups that ran a prompt chain leave the mixer queue loop without another fetch (atomic round trip + 2 LDS barriers off the critical path)
# speedup vs baseline: 1.0320x; 1.0036x over previous
;     __device__ __forceinline__ int tid_() const { return wave * 64 + lane_id(); }
; #define HG_BAR() do { asm volatile("s_waitcnt lgkmcnt(0)" ::: "memory"); __builtin_amdgcn_s_barrier(); asm volatile("" ::: "memory"); } while (0)
; __device__ __forceinline__ void phase_mixers(Frame& F, int layer, int qslot) {
;     ...
;     for (;;) {
;         if (F.tid_() == 0) F.MISC[4] = __hip_atomic_fetch_add(head, 1u, __ATOMIC_RELAXED, __HIP_MEMORY_SCOPE_AGENT);
;         HG_BAR();
;         int u = (int)F.MISC[4];
;         HG_BAR();
;         if (u >= U_TOTAL) break;
.LBB0_559:
	s_cmp_eq_u32 s100, 2
	s_cbranch_scc1 .LBB0_881
	s_cmp_lg_u32 s100, 0
	s_cbranch_scc1 .Ldv_q
	s_mov_b32 s100, 1
	s_cmpk_lt_u32 s101, 64
	s_cbranch_scc1 .Ldv_q
	s_sleep 100

;     __device__ __forceinline__ int tid_() const { return wave * 64 + lane_id(); }
; #define HG_BAR() do { asm volatile("s_waitcnt lgkmcnt(0)" ::: "memory"); __builtin_amdgcn_s_barrier(); asm volatile("" ::: "memory"); } while (0)
; __device__ __forceinline__ void phase_mixers(Frame& F, int layer, int qslot) {
;     ...
;         if (F.tid_() == 0) F.MISC[4] = __hip_atomic_fetch_add(head, 1u, __ATOMIC_RELAXED, __HIP_MEMORY_SCOPE_AGENT);
;         HG_BAR();
;         int u = (int)F.MISC[4];
;         HG_BAR();
;         if (u >= U_TOTAL) break;
;         if (u >= U0_HGS && u < U0_POOL) u = u < U0_HGS + sb::NUNITS ? u + U_HG_S : u - sb::NUNITS;
;         if (u < U0_ATT) { const bool smp = u >= U0_HGS; const int x = smp ? u - U0_HGS : u; hg::chain(F, layer, smp, x >> 3, x & 7); }
;         else if (u < U0_POOL) { const int x = u - U0_ATT; if (x < sb::NU_P) sb::block_unit<1>(F, layer, x); else sb::block_unit<4>(F, layer, x - sb::NU_P); }
;         else pl::unit(F, layer, u - U0_POOL);
.LBB0_563:
	s_or_b64 exec, exec, s[8:9]
	v_readlane_b32 s8, v241, 48
	s_waitcnt lgkmcnt(0)
	s_barrier
	s_nop 0
	v_mov_b32_e32 v0, s8
	ds_read_b32 v0, v0
	s_waitcnt lgkmcnt(0)
	s_barrier
	s_movk_i32 s8, 0x65f
	s_waitcnt lgkmcnt(0)
	v_cmp_lt_i32_e32 vcc, s8, v0
	v_readfirstlane_b32 s13, v0
	s_mov_b64 s[8:9], -1
	s_cbranch_vccnz .LBB0_558
	s_cmpk_lt_u32 s13, 64
	s_cselect_b32 s100, 2, s100
	s_sub_i32 s8, s13, 64
	s_cmpk_lt_i32 s13, 0x2c0
	s_movk_i32 s9, 0xfd80
	s_cselect_b32 s9, 0x100, s9
	s_cmpk_lt_u32 s8, 0x380
	s_cselect_b32 s12, s9, 0
	s_add_i32 s12, s12, s13
	s_cmpk_gt_i32 s12, 0x13f
	s_mov_b64 s[8:9], -1
	s_cbranch_scc0 .LBB0_750
	s_cmpk_gt_u32 s12, 0x3bf
	s_cbranch_scc0 .LBB0_683
	v_mov_b32_e32 v0, v173
	s_add_i32 s15, s12, 0xfffffc40
	s_cmpk_gt_u32 s15, 0x21f
	v_mbcnt_lo_u32_b32 v0, -1, v0
	v_mbcnt_hi_u32_b32 v0, -1, v0
	v_readlane_b32 s8, v241, 21
	s_cselect_b64 s[56:57], -1, 0
	s_cmpk_lt_u32 s15, 0x220
	v_add_u32_e32 v40, s8, v0
	s_cselect_b64 s[8:9], -1, 0
	s_mov_b64 s[26:27], -1
	s_and_b64 vcc, exec, s[56:57]
	s_cbranch_vccnz .LBB0_570
	s_lshr_b32 s14, s15, 2
	s_mul_i32 s15, s15, 0xf0f1
	s_lshr_b32 s20, s15, 22
	s_mul_i32 s15, s20, 0xffffffef
	s_add_i32 s15, s15, s14
	s_lshl_b32 s14, s15, 7
	s_movk_i32 s24, 0x810
	s_cbranch_execz .LBB0_571
